# block-rank computation between the two attention mixers vectorised (4 table loads + ballots instead of 128 dependent scalar-loop round trips)
# speedup vs baseline: 1.0506x; 1.0068x over previous
; __device__ __forceinline__ void phase_attn(const Args& a, LAS unsigned char* lds, int wid, int lane) {
;     ...
;     int pos = 0;
;     { const int* xt = (const int*)(ws + WS_XCC); const int me = (int)blockIdx.x, myx = xt[me];
;       for (int i = 0; i < (int)gridDim.x; ++i) { const int x = xt[i]; pos += (x < myx || (x == myx && i < me)) ? 1 : 0; } }
;     pos = __builtin_amdgcn_readfirstlane(pos);
.LBB0_466:
	v_readlane_b32 s78, v254, 36
	s_waitcnt vmcnt(0) lgkmcnt(0)
	v_readlane_b32 s79, v254, 37
	v_readlane_b32 s0, v254, 0
	s_ashr_i32 s79, s78, 31
	v_readlane_b32 s2, v254, 2
	v_readlane_b32 s96, v254, 32
	s_cmp_lt_i32 s2, 1
	v_readlane_b32 s77, v254, 35
	v_readlane_b32 s85, v254, 34
	v_readlane_b32 s97, v254, 33
	s_waitcnt lgkmcnt(0)
	s_barrier
	v_readlane_b32 s1, v254, 1
	v_readlane_b32 s3, v254, 3
	s_cbranch_scc1 .LBB0_474
	v_readlane_b32 s4, v254, 0
	v_readlane_b32 s5, v254, 1
	s_add_u32 s10, s4, 0xc0000
	s_addc_u32 s11, s5, 0
	s_lshl_b64 s[0:1], s[78:79], 2
	s_add_u32 s0, s10, s0
	s_addc_u32 s1, s11, s1
	v_mov_b32_e32 v1, 0
	global_load_dword v0, v1, s[0:1]
	s_mov_b64 s[12:13], exec
	s_mov_b64 exec, -1
	v_readlane_b32 s6, v254, 2
	v_lshlrev_b32_e32 v1, 2, v212
	s_mov_b32 s90, 0
	global_load_dword v2, v1, s[10:11]
	global_load_dword v3, v1, s[10:11] offset:256
	s_waitcnt vmcnt(0)
	v_cmp_lt_i32_e64 s[0:1], v2, v0
	v_cmp_eq_u32_e64 s[2:3], v2, v0
	v_mov_b32_e32 v2, v212
	v_cmp_gt_u32_e64 s[4:5], s78, v2
	v_cmp_gt_u32_e64 s[8:9], s6, v2
	s_nop 1
	s_and_b64 s[2:3], s[2:3], s[4:5]
	s_or_b64 s[0:1], s[0:1], s[2:3]
	s_and_b64 s[0:1], s[0:1], s[8:9]
	s_bcnt1_i32_b64 s2, s[0:1]
	s_add_i32 s90, s90, s2
	v_cmp_lt_i32_e64 s[0:1], v3, v0
	v_cmp_eq_u32_e64 s[2:3], v3, v0
	v_add_u32_e32 v3, 64, v212
	v_cmp_gt_u32_e64 s[4:5], s78, v3
	v_cmp_gt_u32_e64 s[8:9], s6, v3
	s_nop 1
	s_and_b64 s[2:3], s[2:3], s[4:5]
	s_or_b64 s[0:1], s[0:1], s[2:3]
	s_and_b64 s[0:1], s[0:1], s[8:9]
	s_bcnt1_i32_b64 s2, s[0:1]
	s_add_i32 s90, s90, s2
	global_load_dword v2, v1, s[10:11] offset:512
	global_load_dword v3, v1, s[10:11] offset:768
	s_waitcnt vmcnt(0)
	v_cmp_lt_i32_e64 s[0:1], v2, v0
	v_cmp_eq_u32_e64 s[2:3], v2, v0
	v_add_u32_e32 v2, 128, v212
	v_cmp_gt_u32_e64 s[4:5], s78, v2
	v_cmp_gt_u32_e64 s[8:9], s6, v2
	s_nop 1
	s_and_b64 s[2:3], s[2:3], s[4:5]
	s_or_b64 s[0:1], s[0:1], s[2:3]
	s_and_b64 s[0:1], s[0:1], s[8:9]
	s_bcnt1_i32_b64 s2, s[0:1]
	s_add_i32 s90, s90, s2
	v_cmp_lt_i32_e64 s[0:1], v3, v0
	v_cmp_eq_u32_e64 s[2:3], v3, v0
	v_add_u32_e32 v3, 192, v212
	v_cmp_gt_u32_e64 s[4:5], s78, v3
	v_cmp_gt_u32_e64 s[8:9], s6, v3
	s_nop 1
	s_and_b64 s[2:3], s[2:3], s[4:5]
	s_or_b64 s[0:1], s[0:1], s[2:3]
	s_and_b64 s[0:1], s[0:1], s[8:9]
	s_bcnt1_i32_b64 s2, s[0:1]
	s_add_i32 s90, s90, s2
	s_mov_b64 exec, s[12:13]
	v_readlane_b32 s0, v254, 0
	v_readlane_b32 s1, v254, 1
	v_readlane_b32 s2, v254, 2
	v_readlane_b32 s3, v254, 3
	s_nop 3
